# attention loop back-edge rotation: loop-carried v_mov ahead of the barrier, single taken conditional branch as back edge
# speedup vs baseline: 1.0018x; 1.0018x over previous
; __device__ __forceinline__ void attn_block(const Bases& B, const BlockRef& cur, const BlockRef& nxt, LAS char* lds, Seam& S, int tid) {
;     ...
;     for (int t = 1; t + 1 < NT; t += 2) {
;         HALF_STEP(pB0, pB1, mnB, alB, pA0, pA1, alA, t, 1, 0);
;         HALF_STEP(pA0, pA1, mnA, alA, pB0, pB1, alB, t + 1, 0, 1);
.Lattn_f2_norsc:
	s_add_i32 s4, s74, 1
	s_cmp_lg_u32 s74, 2
	s_cselect_b32 s74, s4, 0
	s_addk_i32 s96, 0x80
	v_mov_b32_e32 v183, v188
	s_cmp_lt_u32 s75, s87
	s_waitcnt lgkmcnt(0)
	s_barrier
	s_cbranch_scc1 .LBB0_506
	s_branch .LBB0_524

; __device__ __forceinline__ void partialSM(f32x16& p0, f32x16& p1, float& m_reg, float& mn, float& alpha) {
;     ...
;     if (__builtin_expect(__all((pmax - m_reg) * ATT_SCALE <= THR), 1)) { mn = m_reg; alpha = 1.f; }
;     else { mn = fmaxf(m_reg, pmax); alpha = __builtin_amdgcn_exp2f((m_reg - mn) * C2); m_reg = mn; }
;     const float mnL = -mn * C2;
; #pragma unroll
;     for (int r = 0; r < 16; ++r) p0[r] = fmaf(p0[r], C2, mnL);
; #pragma unroll
;     for (int r = 0; r < 16; ++r) p1[r] = fmaf(p1[r], C2, mnL);
; #pragma unroll
;     for (int r = 0; r < 16; ++r) p0[r] = __builtin_amdgcn_exp2f(p0[r]);
; }
; __device__ __forceinline__ void finishSM(f32x16& p0, f32x16& p1, float alpha, float& l_reg, bf16x8& pa0, bf16x8& pa1, bf16x8& pa2, bf16x8& pa3) {
; #pragma unroll
;     for (int r = 0; r < 16; ++r) p1[r] = __builtin_amdgcn_exp2f(p1[r]);
;     float ps = 0;
; #pragma unroll
;     for (int r = 0; r < 16; ++r) ps += p0[r];
; #pragma unroll
;     for (int r = 0; r < 16; ++r) ps += p1[r];
;     { auto rr = __builtin_amdgcn_permlane32_swap(__float_as_uint(ps), __float_as_uint(ps), false, false);
;       ps = __uint_as_float(rr[0]) + __uint_as_float(rr[1]); }
;     l_reg = l_reg * alpha + ps;
; __device__ __forceinline__ void attn_block(const Bases& B, const BlockRef& cur, const BlockRef& nxt, LAS char* lds, Seam& S, int tid) {
;     ...
;     for (int t = 1; t + 1 < NT; t += 2) {
;         HALF_STEP(pB0, pB1, mnB, alB, pA0, pA1, alA, t, 1, 0);
;         HALF_STEP(pA0, pA1, mnA, alA, pB0, pB1, alB, t + 1, 0, 1);
.LBB0_522:
	v_cndmask_b32_e64 v185, v130, v0, s[10:11]
	v_mul_f32_e32 v0, 0xbdd53b94, v185
	v_fmamk_f32 v82, v82, 0x3dd53b94, v0
	v_fmamk_f32 v83, v83, 0x3dd53b94, v0
	v_fmamk_f32 v84, v84, 0x3dd53b94, v0
	v_fmamk_f32 v85, v85, 0x3dd53b94, v0
	v_fmamk_f32 v86, v86, 0x3dd53b94, v0
	v_fmamk_f32 v87, v87, 0x3dd53b94, v0
	v_fmamk_f32 v88, v88, 0x3dd53b94, v0
	v_fmamk_f32 v89, v89, 0x3dd53b94, v0
	v_fmamk_f32 v90, v90, 0x3dd53b94, v0
	v_fmamk_f32 v91, v91, 0x3dd53b94, v0
	v_fmamk_f32 v92, v92, 0x3dd53b94, v0
	v_fmamk_f32 v93, v93, 0x3dd53b94, v0
	v_fmamk_f32 v94, v94, 0x3dd53b94, v0
	v_fmamk_f32 v95, v95, 0x3dd53b94, v0
	v_fmamk_f32 v96, v96, 0x3dd53b94, v0
	v_fmamk_f32 v97, v97, 0x3dd53b94, v0
	v_exp_f32_e32 v205, v82
	v_exp_f32_e32 v207, v83
	v_exp_f32_e32 v203, v84
	v_exp_f32_e32 v206, v85
	v_exp_f32_e32 v202, v86
	v_exp_f32_e32 v204, v87
	v_exp_f32_e32 v200, v88
	v_exp_f32_e32 v201, v89
	v_exp_f32_e32 v197, v90
	v_exp_f32_e32 v199, v91
	v_exp_f32_e32 v196, v92
	v_exp_f32_e32 v198, v93
	v_exp_f32_e32 v193, v94
	v_exp_f32_e32 v195, v95
	v_exp_f32_e32 v192, v96
	v_exp_f32_e32 v194, v97
	s_add_i32 s4, s74, 1
	v_pk_fma_f32 v[164:165], v[66:67], s[80:81], v[0:1] op_sel_hi:[1,0,0]
	v_pk_fma_f32 v[162:163], v[68:69], s[80:81], v[0:1] op_sel_hi:[1,0,0]
	v_pk_fma_f32 v[160:161], v[70:71], s[80:81], v[0:1] op_sel_hi:[1,0,0]
	v_pk_fma_f32 v[158:159], v[72:73], s[80:81], v[0:1] op_sel_hi:[1,0,0]
	v_pk_fma_f32 v[156:157], v[74:75], s[80:81], v[0:1] op_sel_hi:[1,0,0]
	v_pk_fma_f32 v[154:155], v[76:77], s[80:81], v[0:1] op_sel_hi:[1,0,0]
	v_pk_fma_f32 v[152:153], v[78:79], s[80:81], v[0:1] op_sel_hi:[1,0,0]
	v_pk_fma_f32 v[150:151], v[80:81], s[80:81], v[0:1] op_sel_hi:[1,0,0]
	v_add_f32_e32 v0, v186, v187
	s_cmp_lg_u32 s74, 2
	v_fmac_f32_e32 v0, v183, v181
	v_add_f32_e32 v181, v190, v191
	s_cselect_b32 s74, s4, 0
	s_addk_i32 s96, 0x80
	v_fmac_f32_e32 v181, v0, v189
	v_mov_b32_e32 v183, v188
	s_cmp_lt_u32 s75, s87
	v_add_u32_e32 v184, 0xffffff80, v184
	s_waitcnt lgkmcnt(0)
	s_barrier
	s_cbranch_scc1 .LBB0_506
	s_branch .LBB0_524
